# gldsfirst
# speedup vs baseline: 1.0118x; 1.0024x over previous
; #define PG8_STAGE(bufoff, gbase, voff) do { _Pragma("unroll") for (int _i = 0; _i < 2; ++_i) \
;         __builtin_amdgcn_global_load_lds((const unsigned*)((const char*)(gbase) + (voff)[_i]), (LAS unsigned*)(lds + (bufoff) + ldsw + _i * 8192), 16, 0, 0); } while (0)
; #define PG8_LDA(dst, b, h) do { _Pragma("unroll") for (int m = 0; m < 4; ++m) _Pragma("unroll") for (int k = 0; k < 2; ++k) dst[m][k] = *(const LAS bf16x8*)(lds + PG8_SA(b, h) + aoff + m * 2048 + k * 1024); } while (0)
; #define PG8_LDB(dst, b, h) do { _Pragma("unroll") for (int n = 0; n < 2; ++n) _Pragma("unroll") for (int k = 0; k < 2; ++k) dst[n][k] = *(const LAS bf16x8*)(lds + PG8_SB(b, h) + boff + n * 2048 + k * 1024); } while (0)
; #define PG8_MMA(ai, bj, At, Bt) do { __builtin_amdgcn_s_setprio(1); _Pragma("unroll") for (int m = 0; m < 4; ++m) _Pragma("unroll") for (int n = 0; n < 2; ++n) _Pragma("unroll") for (int k = 0; k < 2; ++k) \
;         acc[ai][bj][m][n] = __builtin_amdgcn_mfma_f32_16x16x32_bf16(Bt[n][k], At[m][k], acc[ai][bj][m][n], 0, 0, 0); __builtin_amdgcn_s_setprio(0); } while (0)
; #define PG8_WAIT_V(n) asm volatile("s_waitcnt vmcnt(" #n ")" ::: "memory")
; #define PG8_WAIT_L(n) asm volatile("s_waitcnt lgkmcnt(" #n ")" ::: "memory")
; #define PG8_BAR __builtin_amdgcn_s_barrier()
; template <class Epi, class Job>
; __device__ __forceinline__ void gemm_phase(LAS unsigned char* lds, const Job& S, const Epi& E) {
;     ...
;             const bool last = (t == nt - 2);
;             const char* a1 = cA + (size_t)(t + 1) * kstep;
;             const char* a2 = last ? nA : cA + (size_t)(t + 2) * kstep; const char* b2 = last ? nB : cB + (size_t)(t + 2) * kstep;
;             const char* a3 = a2 + kstep; const char* b3 = b2 + kstep;
;             PG8_LDB(B0, 0, 0); PG8_SCHED; PG8_LDA(At, 0, 0); PG8_STAGE(PG8_SA(1, 1), a1 + hstepA, voffA);
;             PG8_WAIT_L(8); PG8_BAR; PG8_WAIT_L(0); PG8_MMA(0, 0, At, B0); PG8_BAR; PG8_SCHED;
;             PG8_LDB(B1, 0, 1); PG8_STAGE(PG8_SB(0, 0), b2, voffB);
;             PG8_BAR; PG8_WAIT_L(0); PG8_MMA(0, 1, At, B1); PG8_BAR;
;             PG8_LDA(At, 0, 1); PG8_STAGE(PG8_SA(0, 0), a2, voffA);
;             PG8_BAR; PG8_WAIT_L(0); PG8_MMA(1, 0, At, B0); PG8_BAR; PG8_SCHED;
;             PG8_STAGE(PG8_SB(0, 1), b2 + hstepB, voffB);
;             PG8_WAIT_V(6); PG8_BAR; PG8_MMA(1, 1, At, B1); PG8_BAR;
.LBB0_186:
	s_add_i32 m0, s52, 0xc000
	s_nop 0
	global_load_lds_dwordx4 v144, s[28:29]
	s_add_i32 m0, s52, 0xe000
	s_nop 0
	global_load_lds_dwordx4 v146, s[28:29]
	s_add_u32 s36, s28, 0xfff00080
	s_addc_u32 s37, s29, -1
	s_cmp_eq_u32 s68, 60
	s_cselect_b32 s47, s23, s37
	s_cselect_b32 s46, s22, s36
	s_cselect_b32 s37, s25, s67
	s_cselect_b32 s36, s24, s27
	ds_read_b128 v[190:193], v155 offset:1024
	ds_read_b128 v[198:201], v155 offset:3072
	ds_read_b128 v[206:209], v155 offset:5120
	ds_read_b128 v[214:217], v155 offset:7168
	s_waitcnt lgkmcnt(8)
	s_barrier
	s_waitcnt lgkmcnt(0)
	s_setprio 1
	v_mfma_f32_16x16x32_bf16 v[124:127], v[158:161], v[186:189], v[124:127]
	ds_read_b128 v[218:221], v156
	v_mfma_f32_16x16x32_bf16 v[120:123], v[178:181], v[186:189], v[120:123]
	v_mfma_f32_16x16x32_bf16 v[112:115], v[158:161], v[194:197], v[112:115]
	ds_read_b128 v[222:225], v156 offset:1024
	v_mfma_f32_16x16x32_bf16 v[104:107], v[178:181], v[194:197], v[104:107]
	v_mfma_f32_16x16x32_bf16 v[100:103], v[158:161], v[202:205], v[100:103]
	ds_read_b128 v[226:229], v156 offset:2048
	v_mfma_f32_16x16x32_bf16 v[92:95], v[178:181], v[202:205], v[92:95]
	v_mfma_f32_16x16x32_bf16 v[84:87], v[158:161], v[210:213], v[84:87]
	ds_read_b128 v[230:233], v156 offset:3072
	v_mfma_f32_16x16x32_bf16 v[76:79], v[178:181], v[210:213], v[76:79]
	v_mfma_f32_16x16x32_bf16 v[124:127], v[174:177], v[190:193], v[124:127]
	v_mfma_f32_16x16x32_bf16 v[120:123], v[182:185], v[190:193], v[120:123]
	v_mfma_f32_16x16x32_bf16 v[112:115], v[174:177], v[198:201], v[112:115]
	v_mfma_f32_16x16x32_bf16 v[104:107], v[182:185], v[198:201], v[104:107]
	v_mfma_f32_16x16x32_bf16 v[100:103], v[174:177], v[206:209], v[100:103]
	v_mfma_f32_16x16x32_bf16 v[92:95], v[182:185], v[206:209], v[92:95]
	v_mfma_f32_16x16x32_bf16 v[84:87], v[174:177], v[214:217], v[84:87]
	v_mfma_f32_16x16x32_bf16 v[76:79], v[182:185], v[214:217], v[76:79]
	s_setprio 0
	s_barrier
	s_add_i32 s69, s60, s49
	s_mov_b32 m0, s69
	s_nop 0
	global_load_lds_dwordx4 v136, s[36:37]
	s_add_i32 m0, s69, 0x2000
	s_nop 0
	global_load_lds_dwordx4 v140, s[36:37]
	s_barrier
	s_waitcnt lgkmcnt(0)
	s_setprio 1
	v_mfma_f32_16x16x32_bf16 v[116:119], v[218:221], v[186:189], v[116:119]
	v_mfma_f32_16x16x32_bf16 v[108:111], v[226:229], v[186:189], v[108:111]
	v_mfma_f32_16x16x32_bf16 v[96:99], v[218:221], v[194:197], v[96:99]
	v_mfma_f32_16x16x32_bf16 v[88:91], v[226:229], v[194:197], v[88:91]
	v_mfma_f32_16x16x32_bf16 v[80:83], v[218:221], v[202:205], v[80:83]
	v_mfma_f32_16x16x32_bf16 v[72:75], v[226:229], v[202:205], v[72:75]
	v_mfma_f32_16x16x32_bf16 v[68:71], v[218:221], v[210:213], v[68:71]
	v_mfma_f32_16x16x32_bf16 v[64:67], v[226:229], v[210:213], v[64:67]
	v_mfma_f32_16x16x32_bf16 v[116:119], v[222:225], v[190:193], v[116:119]
	ds_read_b128 v[186:189], v155 offset:16384
	v_mfma_f32_16x16x32_bf16 v[108:111], v[230:233], v[190:193], v[108:111]
	v_mfma_f32_16x16x32_bf16 v[96:99], v[222:225], v[198:201], v[96:99]
	ds_read_b128 v[194:197], v155 offset:18432
	v_mfma_f32_16x16x32_bf16 v[88:91], v[230:233], v[198:201], v[88:91]
	v_mfma_f32_16x16x32_bf16 v[80:83], v[222:225], v[206:209], v[80:83]
	ds_read_b128 v[202:205], v155 offset:20480
	v_mfma_f32_16x16x32_bf16 v[72:75], v[230:233], v[206:209], v[72:75]
	v_mfma_f32_16x16x32_bf16 v[68:71], v[222:225], v[214:217], v[68:71]
	ds_read_b128 v[210:213], v155 offset:22528
	v_mfma_f32_16x16x32_bf16 v[64:67], v[230:233], v[214:217], v[64:67]
	s_setprio 0
	s_mov_b32 m0, s52
	s_mov_b64 s[100:101], s[46:47]
	s_barrier
	global_load_lds_dwordx4 v134, s[46:47]
	s_mov_b32 m0, s53
	s_nop 0
	global_load_lds_dwordx4 v138, s[46:47]
	ds_read_b128 v[190:193], v155 offset:17408
	ds_read_b128 v[198:201], v155 offset:19456
	ds_read_b128 v[206:209], v155 offset:21504
	ds_read_b128 v[214:217], v155 offset:23552
	s_waitcnt vmcnt(8)
	s_barrier
	s_waitcnt lgkmcnt(0)
	s_setprio 1
	v_mfma_f32_16x16x32_bf16 v[60:63], v[158:161], v[186:189], v[60:63]
	v_mfma_f32_16x16x32_bf16 v[56:59], v[178:181], v[186:189], v[56:59]
	v_mfma_f32_16x16x32_bf16 v[52:55], v[158:161], v[194:197], v[52:55]
	v_mfma_f32_16x16x32_bf16 v[44:47], v[178:181], v[194:197], v[44:47]
	v_mfma_f32_16x16x32_bf16 v[36:39], v[158:161], v[202:205], v[36:39]
	v_mfma_f32_16x16x32_bf16 v[28:31], v[178:181], v[202:205], v[28:31]
	v_mfma_f32_16x16x32_bf16 v[20:23], v[158:161], v[210:213], v[20:23]
	v_mfma_f32_16x16x32_bf16 v[12:15], v[178:181], v[210:213], v[12:15]
	v_mfma_f32_16x16x32_bf16 v[60:63], v[174:177], v[190:193], v[60:63]
	v_mfma_f32_16x16x32_bf16 v[56:59], v[182:185], v[190:193], v[56:59]
	v_mfma_f32_16x16x32_bf16 v[52:55], v[174:177], v[198:201], v[52:55]
	v_mfma_f32_16x16x32_bf16 v[44:47], v[182:185], v[198:201], v[44:47]
	v_mfma_f32_16x16x32_bf16 v[36:39], v[174:177], v[206:209], v[36:39]
	v_mfma_f32_16x16x32_bf16 v[28:31], v[182:185], v[206:209], v[28:31]
	v_mfma_f32_16x16x32_bf16 v[20:23], v[174:177], v[214:217], v[20:23]
	v_mfma_f32_16x16x32_bf16 v[12:15], v[182:185], v[214:217], v[12:15]
	s_setprio 0
	s_barrier
	s_add_u32 s70, s36, 0x100000
	s_addc_u32 s71, s37, 0
	s_add_i32 s69, s61, s49
	s_mov_b32 m0, s69
	s_nop 0
	global_load_lds_dwordx4 v136, s[70:71]
	s_add_i32 m0, s69, 0x2000
	s_nop 0
	global_load_lds_dwordx4 v140, s[70:71]
	s_waitcnt vmcnt(6)
	s_barrier
; #define PG8_STAGE(bufoff, gbase, voff) do { _Pragma("unroll") for (int _i = 0; _i < 2; ++_i) \
;         __builtin_amdgcn_global_load_lds((const unsigned*)((const char*)(gbase) + (voff)[_i]), (LAS unsigned*)(lds + (bufoff) + ldsw + _i * 8192), 16, 0, 0); } while (0)
; #define PG8_LDA(dst, b, h) do { _Pragma("unroll") for (int m = 0; m < 4; ++m) _Pragma("unroll") for (int k = 0; k < 2; ++k) dst[m][k] = *(const LAS bf16x8*)(lds + PG8_SA(b, h) + aoff + m * 2048 + k * 1024); } while (0)
; #define PG8_LDB(dst, b, h) do { _Pragma("unroll") for (int n = 0; n < 2; ++n) _Pragma("unroll") for (int k = 0; k < 2; ++k) dst[n][k] = *(const LAS bf16x8*)(lds + PG8_SB(b, h) + boff + n * 2048 + k * 1024); } while (0)
; #define PG8_MMA(ai, bj, At, Bt) do { __builtin_amdgcn_s_setprio(1); _Pragma("unroll") for (int m = 0; m < 4; ++m) _Pragma("unroll") for (int n = 0; n < 2; ++n) _Pragma("unroll") for (int k = 0; k < 2; ++k) \
;         acc[ai][bj][m][n] = __builtin_amdgcn_mfma_f32_16x16x32_bf16(Bt[n][k], At[m][k], acc[ai][bj][m][n], 0, 0, 0); __builtin_amdgcn_s_setprio(0); } while (0)
; #define PG8_WAIT_V(n) asm volatile("s_waitcnt vmcnt(" #n ")" ::: "memory")
; #define PG8_WAIT_L(n) asm volatile("s_waitcnt lgkmcnt(" #n ")" ::: "memory")
; #define PG8_BAR __builtin_amdgcn_s_barrier()
; #define PG8_SCHED __builtin_amdgcn_sched_barrier(0)
; template <class Epi, class Job>
; __device__ __forceinline__ void gemm_phase(LAS unsigned char* lds, const Job& S, const Epi& E) {
;     ...
;             PG8_WAIT_V(6); PG8_BAR; PG8_MMA(1, 1, At, B1); PG8_BAR;
;             PG8_LDB(B0, 1, 0); PG8_SCHED; PG8_LDA(At, 1, 0); PG8_STAGE(PG8_SA(0, 1), a2 + hstepA, voffA);
;             PG8_WAIT_L(8); PG8_BAR; PG8_WAIT_L(0); PG8_MMA(0, 0, At, B0); PG8_BAR; PG8_SCHED;
;             PG8_LDB(B1, 1, 1); PG8_STAGE(PG8_SB(1, 0), b3, voffB);
;             PG8_BAR; PG8_WAIT_L(0); PG8_MMA(0, 1, At, B1); PG8_BAR;
	s_setprio 1
	v_add_u32_e32 v157, 0x18000, v153
	v_mfma_f32_16x16x32_bf16 v[48:51], v[218:221], v[186:189], v[48:51]
	ds_read_b128 v[158:161], v157
	v_mfma_f32_16x16x32_bf16 v[40:43], v[226:229], v[186:189], v[40:43]
	v_mfma_f32_16x16x32_bf16 v[32:35], v[218:221], v[194:197], v[32:35]
	ds_read_b128 v[174:177], v157 offset:1024
	v_mfma_f32_16x16x32_bf16 v[24:27], v[226:229], v[194:197], v[24:27]
	v_mfma_f32_16x16x32_bf16 v[16:19], v[218:221], v[202:205], v[16:19]
	ds_read_b128 v[178:181], v157 offset:2048
	v_mfma_f32_16x16x32_bf16 v[8:11], v[226:229], v[202:205], v[8:11]
	v_mfma_f32_16x16x32_bf16 v[4:7], v[218:221], v[210:213], v[4:7]
	ds_read_b128 v[182:185], v157 offset:3072
	v_mfma_f32_16x16x32_bf16 v[0:3], v[226:229], v[210:213], v[0:3]
	v_mfma_f32_16x16x32_bf16 v[48:51], v[222:225], v[190:193], v[48:51]
	ds_read_b128 v[186:189], v155 offset:32768
	v_mfma_f32_16x16x32_bf16 v[40:43], v[230:233], v[190:193], v[40:43]
	v_mfma_f32_16x16x32_bf16 v[32:35], v[222:225], v[198:201], v[32:35]
	ds_read_b128 v[194:197], v155 offset:34816
	v_mfma_f32_16x16x32_bf16 v[24:27], v[230:233], v[198:201], v[24:27]
	v_mfma_f32_16x16x32_bf16 v[16:19], v[222:225], v[206:209], v[16:19]
	ds_read_b128 v[202:205], v155 offset:36864
	v_mfma_f32_16x16x32_bf16 v[8:11], v[230:233], v[206:209], v[8:11]
	v_mfma_f32_16x16x32_bf16 v[4:7], v[222:225], v[214:217], v[4:7]
	ds_read_b128 v[210:213], v155 offset:38912
	v_mfma_f32_16x16x32_bf16 v[0:3], v[230:233], v[214:217], v[0:3]
	s_setprio 0
	s_add_i32 s69, 0, 0x18000
	v_add_u32_e32 v157, s69, v153
	s_barrier
	s_add_u32 s46, s46, 0x100000
	s_addc_u32 s47, s47, 0
	s_mov_b32 m0, s54
	s_nop 0
	global_load_lds_dwordx4 v134, s[46:47]
	s_mov_b32 m0, s55
	s_nop 0
	global_load_lds_dwordx4 v138, s[46:47]
	ds_read_b128 v[190:193], v155 offset:33792
	ds_read_b128 v[198:201], v155 offset:35840
	ds_read_b128 v[206:209], v155 offset:37888
	ds_read_b128 v[214:217], v155 offset:39936
	s_waitcnt lgkmcnt(8)
	s_barrier
	s_waitcnt lgkmcnt(0)
	s_setprio 1
	v_add_u32_e32 v157, 0x1c000, v153
	v_mfma_f32_16x16x32_bf16 v[124:127], v[158:161], v[186:189], v[124:127]
	ds_read_b128 v[218:221], v157
	v_mfma_f32_16x16x32_bf16 v[120:123], v[178:181], v[186:189], v[120:123]
	v_mfma_f32_16x16x32_bf16 v[112:115], v[158:161], v[194:197], v[112:115]
	ds_read_b128 v[222:225], v157 offset:1024
	v_mfma_f32_16x16x32_bf16 v[104:107], v[178:181], v[194:197], v[104:107]
	v_mfma_f32_16x16x32_bf16 v[100:103], v[158:161], v[202:205], v[100:103]
	ds_read_b128 v[226:229], v157 offset:2048
	v_mfma_f32_16x16x32_bf16 v[92:95], v[178:181], v[202:205], v[92:95]
	v_mfma_f32_16x16x32_bf16 v[84:87], v[158:161], v[210:213], v[84:87]
	ds_read_b128 v[230:233], v157 offset:3072
	v_mfma_f32_16x16x32_bf16 v[76:79], v[178:181], v[210:213], v[76:79]
	v_mfma_f32_16x16x32_bf16 v[124:127], v[174:177], v[190:193], v[124:127]
	v_mfma_f32_16x16x32_bf16 v[120:123], v[182:185], v[190:193], v[120:123]
	v_mfma_f32_16x16x32_bf16 v[112:115], v[174:177], v[198:201], v[112:115]
	v_mfma_f32_16x16x32_bf16 v[104:107], v[182:185], v[198:201], v[104:107]
	v_mfma_f32_16x16x32_bf16 v[100:103], v[174:177], v[206:209], v[100:103]
	v_mfma_f32_16x16x32_bf16 v[92:95], v[182:185], v[206:209], v[92:95]
	v_mfma_f32_16x16x32_bf16 v[84:87], v[174:177], v[214:217], v[84:87]
	v_mfma_f32_16x16x32_bf16 v[76:79], v[182:185], v[214:217], v[76:79]
	s_setprio 0
	s_barrier
	s_add_i32 s46, 0, 0x1c000
	s_add_i32 s47, s69, s49
	v_add_u32_e32 v157, s46, v153
	s_add_u32 s98, s36, s10
	s_addc_u32 s99, s37, s11
	s_mov_b32 m0, s47
	s_nop 0
	global_load_lds_dwordx4 v136, s[98:99]
	s_add_i32 m0, s47, 0x2000
	s_nop 0
	global_load_lds_dwordx4 v140, s[98:99]
	s_barrier
	s_waitcnt lgkmcnt(0)
	s_setprio 1
	v_mfma_f32_16x16x32_bf16 v[116:119], v[218:221], v[186:189], v[116:119]
	v_mfma_f32_16x16x32_bf16 v[108:111], v[226:229], v[186:189], v[108:111]
	v_mfma_f32_16x16x32_bf16 v[96:99], v[218:221], v[194:197], v[96:99]
	v_mfma_f32_16x16x32_bf16 v[88:91], v[226:229], v[194:197], v[88:91]
	v_mfma_f32_16x16x32_bf16 v[80:83], v[218:221], v[202:205], v[80:83]
	v_mfma_f32_16x16x32_bf16 v[72:75], v[226:229], v[202:205], v[72:75]
	v_mfma_f32_16x16x32_bf16 v[68:71], v[218:221], v[210:213], v[68:71]
	v_mfma_f32_16x16x32_bf16 v[64:67], v[226:229], v[210:213], v[64:67]
	v_mfma_f32_16x16x32_bf16 v[116:119], v[222:225], v[190:193], v[116:119]
	ds_read_b128 v[186:189], v155 offset:49152
	v_mfma_f32_16x16x32_bf16 v[108:111], v[230:233], v[190:193], v[108:111]
	v_mfma_f32_16x16x32_bf16 v[96:99], v[222:225], v[198:201], v[96:99]
	ds_read_b128 v[194:197], v155 offset:51200
	v_mfma_f32_16x16x32_bf16 v[88:91], v[230:233], v[198:201], v[88:91]
	v_mfma_f32_16x16x32_bf16 v[80:83], v[222:225], v[206:209], v[80:83]
	ds_read_b128 v[202:205], v155 offset:53248
	v_mfma_f32_16x16x32_bf16 v[72:75], v[230:233], v[206:209], v[72:75]
	v_mfma_f32_16x16x32_bf16 v[68:71], v[222:225], v[214:217], v[68:71]
	ds_read_b128 v[210:213], v155 offset:55296
	v_mfma_f32_16x16x32_bf16 v[64:67], v[230:233], v[214:217], v[64:67]
	s_setprio 0
	s_mov_b32 m0, s56
	s_add_u32 s100, s100, s10
	s_addc_u32 s101, s101, s11
	s_barrier
; #define PG8_STAGE(bufoff, gbase, voff) do { _Pragma("unroll") for (int _i = 0; _i < 2; ++_i) \
;         __builtin_amdgcn_global_load_lds((const unsigned*)((const char*)(gbase) + (voff)[_i]), (LAS unsigned*)(lds + (bufoff) + ldsw + _i * 8192), 16, 0, 0); } while (0)
; #define PG8_LDA(dst, b, h) do { _Pragma("unroll") for (int m = 0; m < 4; ++m) _Pragma("unroll") for (int k = 0; k < 2; ++k) dst[m][k] = *(const LAS bf16x8*)(lds + PG8_SA(b, h) + aoff + m * 2048 + k * 1024); } while (0)
; #define PG8_MMA(ai, bj, At, Bt) do { __builtin_amdgcn_s_setprio(1); _Pragma("unroll") for (int m = 0; m < 4; ++m) _Pragma("unroll") for (int n = 0; n < 2; ++n) _Pragma("unroll") for (int k = 0; k < 2; ++k) \
;         acc[ai][bj][m][n] = __builtin_amdgcn_mfma_f32_16x16x32_bf16(Bt[n][k], At[m][k], acc[ai][bj][m][n], 0, 0, 0); __builtin_amdgcn_s_setprio(0); } while (0)
; #define PG8_WAIT_V(n) asm volatile("s_waitcnt vmcnt(" #n ")" ::: "memory")
; #define PG8_WAIT_L(n) asm volatile("s_waitcnt lgkmcnt(" #n ")" ::: "memory")
; #define PG8_BAR __builtin_amdgcn_s_barrier()
; #define PG8_SCHED __builtin_amdgcn_sched_barrier(0)
;     __device__ __forceinline__ void operator()(const f32x4 (&acc)[2][2][4][2], const Unit& u, int wr, int wc, int fr, int fq) const {
;     ...
;         if (u.ocol < 6144) { const int sect = u.ocol >> 11, hh0 = (u.ocol & 2047) >> 7, b = u.orow >= SEQ ? 1 : 0;
;             base = qkv + (size_t)sect * MTOK * 2048 + ((size_t)(b * 16 + hh0) * SEQ + (row0 & (SEQ - 1))) * 128 + wc * 32 + 8 * fq; rstride = 128; bjstride = (size_t)SEQ * 128; }
;         else { base = proj2 + (size_t)row0 * NP2 + (u.ocol - 6144) + wc * 32 + 8 * fq; rstride = NP2; bjstride = HALF; }
; template <class Epi, class Job>
; __device__ __forceinline__ void gemm_phase(LAS unsigned char* lds, const Job& S, const Epi& E) {
;     ...
;             PG8_LDA(At, 1, 1); PG8_STAGE(PG8_SA(1, 0), a3, voffA);
;             PG8_BAR; PG8_WAIT_L(0); PG8_MMA(1, 0, At, B0); PG8_BAR; PG8_SCHED;
;             PG8_STAGE(PG8_SB(1, 1), b3 + hstepB, voffB);
;             PG8_WAIT_V(6); PG8_BAR; PG8_MMA(1, 1, At, B1); PG8_BAR;
	global_load_lds_dwordx4 v134, s[100:101]
	s_mov_b32 m0, s57
	s_nop 0
	global_load_lds_dwordx4 v138, s[100:101]
	ds_read_b128 v[190:193], v155 offset:50176
	ds_read_b128 v[198:201], v155 offset:52224
	ds_read_b128 v[206:209], v155 offset:54272
	ds_read_b128 v[214:217], v155 offset:56320
	s_waitcnt vmcnt(8)
	s_barrier
	s_waitcnt lgkmcnt(0)
	s_setprio 1
	v_mfma_f32_16x16x32_bf16 v[60:63], v[158:161], v[186:189], v[60:63]
	v_mfma_f32_16x16x32_bf16 v[56:59], v[178:181], v[186:189], v[56:59]
	v_mfma_f32_16x16x32_bf16 v[52:55], v[158:161], v[194:197], v[52:55]
	v_mfma_f32_16x16x32_bf16 v[44:47], v[178:181], v[194:197], v[44:47]
	v_mfma_f32_16x16x32_bf16 v[36:39], v[158:161], v[202:205], v[36:39]
	v_mfma_f32_16x16x32_bf16 v[28:31], v[178:181], v[202:205], v[28:31]
	v_mfma_f32_16x16x32_bf16 v[20:23], v[158:161], v[210:213], v[20:23]
	v_mfma_f32_16x16x32_bf16 v[12:15], v[178:181], v[210:213], v[12:15]
	v_mfma_f32_16x16x32_bf16 v[60:63], v[174:177], v[190:193], v[60:63]
	v_mfma_f32_16x16x32_bf16 v[56:59], v[182:185], v[190:193], v[56:59]
	v_mfma_f32_16x16x32_bf16 v[52:55], v[174:177], v[198:201], v[52:55]
	v_mfma_f32_16x16x32_bf16 v[44:47], v[182:185], v[198:201], v[44:47]
	v_mfma_f32_16x16x32_bf16 v[36:39], v[174:177], v[206:209], v[36:39]
	v_mfma_f32_16x16x32_bf16 v[28:31], v[182:185], v[206:209], v[28:31]
	v_mfma_f32_16x16x32_bf16 v[20:23], v[174:177], v[214:217], v[20:23]
	v_mfma_f32_16x16x32_bf16 v[12:15], v[182:185], v[214:217], v[12:15]
	s_setprio 0
	s_barrier
	s_add_u32 s36, s36, 0x100080
	s_addc_u32 s37, s37, 0
	s_add_i32 s46, s46, s49
	s_mov_b32 m0, s46
	s_nop 0
	global_load_lds_dwordx4 v136, s[36:37]
	s_add_i32 m0, s46, 0x2000
	s_nop 0
	global_load_lds_dwordx4 v140, s[36:37]
	s_waitcnt vmcnt(6)
	s_barrier
	s_setprio 1
	v_mfma_f32_16x16x32_bf16 v[48:51], v[218:221], v[186:189], v[48:51]
	ds_read_b128 v[158:161], v154
	v_mfma_f32_16x16x32_bf16 v[40:43], v[226:229], v[186:189], v[40:43]
	v_mfma_f32_16x16x32_bf16 v[32:35], v[218:221], v[194:197], v[32:35]
	ds_read_b128 v[174:177], v154 offset:1024
	v_mfma_f32_16x16x32_bf16 v[24:27], v[226:229], v[194:197], v[24:27]
	v_mfma_f32_16x16x32_bf16 v[16:19], v[218:221], v[202:205], v[16:19]
	ds_read_b128 v[178:181], v154 offset:2048
	v_mfma_f32_16x16x32_bf16 v[8:11], v[226:229], v[202:205], v[8:11]
	v_mfma_f32_16x16x32_bf16 v[4:7], v[218:221], v[210:213], v[4:7]
	ds_read_b128 v[182:185], v154 offset:3072
	v_mfma_f32_16x16x32_bf16 v[0:3], v[226:229], v[210:213], v[0:3]
	v_mfma_f32_16x16x32_bf16 v[48:51], v[222:225], v[190:193], v[48:51]
	ds_read_b128 v[186:189], v155
	v_mfma_f32_16x16x32_bf16 v[40:43], v[230:233], v[190:193], v[40:43]
	v_mfma_f32_16x16x32_bf16 v[32:35], v[222:225], v[198:201], v[32:35]
	ds_read_b128 v[194:197], v155 offset:2048
	v_mfma_f32_16x16x32_bf16 v[24:27], v[230:233], v[198:201], v[24:27]
	v_mfma_f32_16x16x32_bf16 v[16:19], v[222:225], v[206:209], v[16:19]
	ds_read_b128 v[202:205], v155 offset:4096
	v_mfma_f32_16x16x32_bf16 v[8:11], v[230:233], v[206:209], v[8:11]
	v_mfma_f32_16x16x32_bf16 v[4:7], v[222:225], v[214:217], v[4:7]
	ds_read_b128 v[210:213], v155 offset:6144
	v_mfma_f32_16x16x32_bf16 v[0:3], v[230:233], v[214:217], v[0:3]
	s_setprio 0
	s_add_i32 s68, s68, 2
	s_add_u32 s28, s28, 0x100
	s_addc_u32 s29, s29, 0
	s_add_u32 s27, s27, 0x100
	s_addc_u32 s67, s67, 0
	s_cmp_gt_u32 s68, 61
	s_barrier
	s_cbranch_scc0 .LBB0_186
	s_waitcnt lgkmcnt(0)
	v_add_u32_e32 v157, s66, v131
	s_cmpk_gt_i32 s26, 0x17ff
	s_mov_b64 s[28:29], -1
	s_cbranch_scc0 .LBB0_189
	v_mov_b64_e32 v[150:151], s[20:21]
	v_mad_i64_i32 v[150:151], s[28:29], v157, s62, v[150:151]
	s_mov_b32 s27, s9
	v_lshl_add_u64 v[150:151], s[26:27], 1, v[150:151]
	v_lshl_add_u64 v[150:151], v[150:151], 0, s[12:13]
	s_mov_b64 s[28:29], 0

; #define PG8_STAGE(bufoff, gbase, voff) do { _Pragma("unroll") for (int _i = 0; _i < 2; ++_i) \
;         __builtin_amdgcn_global_load_lds((const unsigned*)((const char*)(gbase) + (voff)[_i]), (LAS unsigned*)(lds + (bufoff) + ldsw + _i * 8192), 16, 0, 0); } while (0)
; #define PG8_LDA(dst, b, h) do { _Pragma("unroll") for (int m = 0; m < 4; ++m) _Pragma("unroll") for (int k = 0; k < 2; ++k) dst[m][k] = *(const LAS bf16x8*)(lds + PG8_SA(b, h) + aoff + m * 2048 + k * 1024); } while (0)
; #define PG8_LDB(dst, b, h) do { _Pragma("unroll") for (int n = 0; n < 2; ++n) _Pragma("unroll") for (int k = 0; k < 2; ++k) dst[n][k] = *(const LAS bf16x8*)(lds + PG8_SB(b, h) + boff + n * 2048 + k * 1024); } while (0)
; #define PG8_MMA(ai, bj, At, Bt) do { __builtin_amdgcn_s_setprio(1); _Pragma("unroll") for (int m = 0; m < 4; ++m) _Pragma("unroll") for (int n = 0; n < 2; ++n) _Pragma("unroll") for (int k = 0; k < 2; ++k) \
;         acc[ai][bj][m][n] = __builtin_amdgcn_mfma_f32_16x16x32_bf16(Bt[n][k], At[m][k], acc[ai][bj][m][n], 0, 0, 0); __builtin_amdgcn_s_setprio(0); } while (0)
; #define PG8_WAIT_V(n) asm volatile("s_waitcnt vmcnt(" #n ")" ::: "memory")
; #define PG8_WAIT_L(n) asm volatile("s_waitcnt lgkmcnt(" #n ")" ::: "memory")
; #define PG8_BAR __builtin_amdgcn_s_barrier()
; template <class Epi, class Job>
; __device__ __forceinline__ void gemm_phase(LAS unsigned char* lds, const Job& S, const Epi& E) {
;     ...
;             const bool last = (t == nt - 2);
;             const char* a1 = cA + (size_t)(t + 1) * kstep;
;             const char* a2 = last ? nA : cA + (size_t)(t + 2) * kstep; const char* b2 = last ? nB : cB + (size_t)(t + 2) * kstep;
;             const char* a3 = a2 + kstep; const char* b3 = b2 + kstep;
;             PG8_LDB(B0, 0, 0); PG8_SCHED; PG8_LDA(At, 0, 0); PG8_STAGE(PG8_SA(1, 1), a1 + hstepA, voffA);
;             PG8_WAIT_L(8); PG8_BAR; PG8_WAIT_L(0); PG8_MMA(0, 0, At, B0); PG8_BAR; PG8_SCHED;
;             PG8_LDB(B1, 0, 1); PG8_STAGE(PG8_SB(0, 0), b2, voffB);
;             PG8_BAR; PG8_WAIT_L(0); PG8_MMA(0, 1, At, B1); PG8_BAR;
;             PG8_LDA(At, 0, 1); PG8_STAGE(PG8_SA(0, 0), a2, voffA);
;             PG8_BAR; PG8_WAIT_L(0); PG8_MMA(1, 0, At, B0); PG8_BAR; PG8_SCHED;
;             PG8_STAGE(PG8_SB(0, 1), b2 + hstepB, voffB);
;             PG8_WAIT_V(6); PG8_BAR; PG8_MMA(1, 1, At, B1); PG8_BAR;
.LBB0_457:
	s_add_i32 m0, s57, 0xc000
	s_nop 0
	global_load_lds_dwordx4 v132, s[36:37]
	s_add_i32 m0, s57, 0xe000
	s_nop 0
	global_load_lds_dwordx4 v142, s[36:37]
	s_add_u32 s46, s36, 0xfff00080
	s_addc_u32 s47, s37, -1
	s_cmp_eq_u32 s81, 60
	s_cselect_b32 s49, s29, s47
	s_cselect_b32 s48, s28, s46
	s_cselect_b32 s47, s31, s80
	s_cselect_b32 s46, s30, s79
	ds_read_b128 v[174:177], v151 offset:1024
	ds_read_b128 v[182:185], v151 offset:3072
	ds_read_b128 v[190:193], v151 offset:5120
	ds_read_b128 v[198:201], v151 offset:7168
	s_waitcnt lgkmcnt(8)
	s_barrier
	s_waitcnt lgkmcnt(0)
	s_setprio 1
	v_mfma_f32_16x16x32_bf16 v[124:127], v[154:157], v[170:173], v[124:127]
	ds_read_b128 v[202:205], v152
	v_mfma_f32_16x16x32_bf16 v[120:123], v[162:165], v[170:173], v[120:123]
	v_mfma_f32_16x16x32_bf16 v[116:119], v[154:157], v[178:181], v[116:119]
	ds_read_b128 v[206:209], v152 offset:1024
	v_mfma_f32_16x16x32_bf16 v[108:111], v[162:165], v[178:181], v[108:111]
	v_mfma_f32_16x16x32_bf16 v[100:103], v[154:157], v[186:189], v[100:103]
	ds_read_b128 v[210:213], v152 offset:2048
	v_mfma_f32_16x16x32_bf16 v[92:95], v[162:165], v[186:189], v[92:95]
	v_mfma_f32_16x16x32_bf16 v[84:87], v[154:157], v[194:197], v[84:87]
	ds_read_b128 v[214:217], v152 offset:3072
	v_mfma_f32_16x16x32_bf16 v[76:79], v[162:165], v[194:197], v[76:79]
	v_mfma_f32_16x16x32_bf16 v[124:127], v[158:161], v[174:177], v[124:127]
	v_mfma_f32_16x16x32_bf16 v[120:123], v[166:169], v[174:177], v[120:123]
	v_mfma_f32_16x16x32_bf16 v[116:119], v[158:161], v[182:185], v[116:119]
	v_mfma_f32_16x16x32_bf16 v[108:111], v[166:169], v[182:185], v[108:111]
	v_mfma_f32_16x16x32_bf16 v[100:103], v[158:161], v[190:193], v[100:103]
	v_mfma_f32_16x16x32_bf16 v[92:95], v[166:169], v[190:193], v[92:95]
	v_mfma_f32_16x16x32_bf16 v[84:87], v[158:161], v[198:201], v[84:87]
	v_mfma_f32_16x16x32_bf16 v[76:79], v[166:169], v[198:201], v[76:79]
	s_setprio 0
	s_barrier
	s_add_i32 s82, s66, s56
	s_mov_b32 m0, s82
	s_nop 0
	global_load_lds_dwordx4 v136, s[46:47]
	s_add_i32 m0, s82, 0x2000
	s_nop 0
	global_load_lds_dwordx4 v140, s[46:47]
	s_barrier
	s_waitcnt lgkmcnt(0)
	s_setprio 1
	v_mfma_f32_16x16x32_bf16 v[112:115], v[202:205], v[170:173], v[112:115]
	v_mfma_f32_16x16x32_bf16 v[104:107], v[210:213], v[170:173], v[104:107]
	v_mfma_f32_16x16x32_bf16 v[96:99], v[202:205], v[178:181], v[96:99]
	v_mfma_f32_16x16x32_bf16 v[88:91], v[210:213], v[178:181], v[88:91]
	v_mfma_f32_16x16x32_bf16 v[80:83], v[202:205], v[186:189], v[80:83]
	v_mfma_f32_16x16x32_bf16 v[72:75], v[210:213], v[186:189], v[72:75]
	v_mfma_f32_16x16x32_bf16 v[68:71], v[202:205], v[194:197], v[68:71]
	v_mfma_f32_16x16x32_bf16 v[64:67], v[210:213], v[194:197], v[64:67]
	v_mfma_f32_16x16x32_bf16 v[112:115], v[206:209], v[174:177], v[112:115]
	ds_read_b128 v[170:173], v151 offset:16384
	v_mfma_f32_16x16x32_bf16 v[104:107], v[214:217], v[174:177], v[104:107]
	v_mfma_f32_16x16x32_bf16 v[96:99], v[206:209], v[182:185], v[96:99]
	ds_read_b128 v[178:181], v151 offset:18432
	v_mfma_f32_16x16x32_bf16 v[88:91], v[214:217], v[182:185], v[88:91]
	v_mfma_f32_16x16x32_bf16 v[80:83], v[206:209], v[190:193], v[80:83]
	ds_read_b128 v[186:189], v151 offset:20480
	v_mfma_f32_16x16x32_bf16 v[72:75], v[214:217], v[190:193], v[72:75]
	v_mfma_f32_16x16x32_bf16 v[68:71], v[206:209], v[198:201], v[68:71]
	ds_read_b128 v[194:197], v151 offset:22528
	v_mfma_f32_16x16x32_bf16 v[64:67], v[214:217], v[198:201], v[64:67]
	s_setprio 0
	s_mov_b32 m0, s57
	s_mov_b64 s[100:101], s[48:49]
	s_barrier
	global_load_lds_dwordx4 v134, s[48:49]
	s_mov_b32 m0, s58
	s_nop 0
	global_load_lds_dwordx4 v138, s[48:49]
	ds_read_b128 v[174:177], v151 offset:17408
	ds_read_b128 v[182:185], v151 offset:19456
	ds_read_b128 v[190:193], v151 offset:21504
	ds_read_b128 v[198:201], v151 offset:23552
	s_waitcnt vmcnt(8)
	s_barrier
	s_waitcnt lgkmcnt(0)
	s_setprio 1
	v_mfma_f32_16x16x32_bf16 v[60:63], v[154:157], v[170:173], v[60:63]
	v_mfma_f32_16x16x32_bf16 v[56:59], v[162:165], v[170:173], v[56:59]
	v_mfma_f32_16x16x32_bf16 v[52:55], v[154:157], v[178:181], v[52:55]
	v_mfma_f32_16x16x32_bf16 v[44:47], v[162:165], v[178:181], v[44:47]
	v_mfma_f32_16x16x32_bf16 v[36:39], v[154:157], v[186:189], v[36:39]
	v_mfma_f32_16x16x32_bf16 v[28:31], v[162:165], v[186:189], v[28:31]
	v_mfma_f32_16x16x32_bf16 v[20:23], v[154:157], v[194:197], v[20:23]
	v_mfma_f32_16x16x32_bf16 v[12:15], v[162:165], v[194:197], v[12:15]
	v_mfma_f32_16x16x32_bf16 v[60:63], v[158:161], v[174:177], v[60:63]
	v_mfma_f32_16x16x32_bf16 v[56:59], v[166:169], v[174:177], v[56:59]
	v_mfma_f32_16x16x32_bf16 v[52:55], v[158:161], v[182:185], v[52:55]
	v_mfma_f32_16x16x32_bf16 v[44:47], v[166:169], v[182:185], v[44:47]
	v_mfma_f32_16x16x32_bf16 v[36:39], v[158:161], v[190:193], v[36:39]
	v_mfma_f32_16x16x32_bf16 v[28:31], v[166:169], v[190:193], v[28:31]
	v_mfma_f32_16x16x32_bf16 v[20:23], v[158:161], v[198:201], v[20:23]
	v_mfma_f32_16x16x32_bf16 v[12:15], v[166:169], v[198:201], v[12:15]
	s_setprio 0
	s_barrier
	s_add_u32 s82, s46, 0x100000
	s_addc_u32 s83, s47, 0
	s_add_i32 s84, s67, s56
	s_mov_b32 m0, s84
	s_nop 0
	global_load_lds_dwordx4 v136, s[82:83]
	s_add_i32 m0, s84, 0x2000
	s_nop 0
	global_load_lds_dwordx4 v140, s[82:83]
	s_waitcnt vmcnt(6)
	s_barrier
; #define PG8_STAGE(bufoff, gbase, voff) do { _Pragma("unroll") for (int _i = 0; _i < 2; ++_i) \
;         __builtin_amdgcn_global_load_lds((const unsigned*)((const char*)(gbase) + (voff)[_i]), (LAS unsigned*)(lds + (bufoff) + ldsw + _i * 8192), 16, 0, 0); } while (0)
; #define PG8_LDA(dst, b, h) do { _Pragma("unroll") for (int m = 0; m < 4; ++m) _Pragma("unroll") for (int k = 0; k < 2; ++k) dst[m][k] = *(const LAS bf16x8*)(lds + PG8_SA(b, h) + aoff + m * 2048 + k * 1024); } while (0)
; #define PG8_LDB(dst, b, h) do { _Pragma("unroll") for (int n = 0; n < 2; ++n) _Pragma("unroll") for (int k = 0; k < 2; ++k) dst[n][k] = *(const LAS bf16x8*)(lds + PG8_SB(b, h) + boff + n * 2048 + k * 1024); } while (0)
; #define PG8_MMA(ai, bj, At, Bt) do { __builtin_amdgcn_s_setprio(1); _Pragma("unroll") for (int m = 0; m < 4; ++m) _Pragma("unroll") for (int n = 0; n < 2; ++n) _Pragma("unroll") for (int k = 0; k < 2; ++k) \
;         acc[ai][bj][m][n] = __builtin_amdgcn_mfma_f32_16x16x32_bf16(Bt[n][k], At[m][k], acc[ai][bj][m][n], 0, 0, 0); __builtin_amdgcn_s_setprio(0); } while (0)
; #define PG8_WAIT_V(n) asm volatile("s_waitcnt vmcnt(" #n ")" ::: "memory")
; #define PG8_WAIT_L(n) asm volatile("s_waitcnt lgkmcnt(" #n ")" ::: "memory")
; #define PG8_BAR __builtin_amdgcn_s_barrier()
; #define PG8_SCHED __builtin_amdgcn_sched_barrier(0)
; template <class Epi, class Job>
; __device__ __forceinline__ void gemm_phase(LAS unsigned char* lds, const Job& S, const Epi& E) {
;     ...
;             PG8_WAIT_V(6); PG8_BAR; PG8_MMA(1, 1, At, B1); PG8_BAR;
;             PG8_LDB(B0, 1, 0); PG8_SCHED; PG8_LDA(At, 1, 0); PG8_STAGE(PG8_SA(0, 1), a2 + hstepA, voffA);
;             PG8_WAIT_L(8); PG8_BAR; PG8_WAIT_L(0); PG8_MMA(0, 0, At, B0); PG8_BAR; PG8_SCHED;
;             PG8_LDB(B1, 1, 1); PG8_STAGE(PG8_SB(1, 0), b3, voffB);
;             PG8_BAR; PG8_WAIT_L(0); PG8_MMA(0, 1, At, B1); PG8_BAR;
;             PG8_LDA(At, 1, 1); PG8_STAGE(PG8_SA(1, 0), a3, voffA);
	s_setprio 1
	v_add_u32_e32 v153, 0x18000, v148
	v_mfma_f32_16x16x32_bf16 v[48:51], v[202:205], v[170:173], v[48:51]
	ds_read_b128 v[154:157], v153
	v_mfma_f32_16x16x32_bf16 v[40:43], v[210:213], v[170:173], v[40:43]
	v_mfma_f32_16x16x32_bf16 v[32:35], v[202:205], v[178:181], v[32:35]
	ds_read_b128 v[158:161], v153 offset:1024
	v_mfma_f32_16x16x32_bf16 v[24:27], v[210:213], v[178:181], v[24:27]
	v_mfma_f32_16x16x32_bf16 v[16:19], v[202:205], v[186:189], v[16:19]
	ds_read_b128 v[162:165], v153 offset:2048
	v_mfma_f32_16x16x32_bf16 v[8:11], v[210:213], v[186:189], v[8:11]
	v_mfma_f32_16x16x32_bf16 v[4:7], v[202:205], v[194:197], v[4:7]
	ds_read_b128 v[166:169], v153 offset:3072
	v_mfma_f32_16x16x32_bf16 v[0:3], v[210:213], v[194:197], v[0:3]
	v_mfma_f32_16x16x32_bf16 v[48:51], v[206:209], v[174:177], v[48:51]
	ds_read_b128 v[170:173], v151 offset:32768
	v_mfma_f32_16x16x32_bf16 v[40:43], v[214:217], v[174:177], v[40:43]
	v_mfma_f32_16x16x32_bf16 v[32:35], v[206:209], v[182:185], v[32:35]
	ds_read_b128 v[178:181], v151 offset:34816
	v_mfma_f32_16x16x32_bf16 v[24:27], v[214:217], v[182:185], v[24:27]
	v_mfma_f32_16x16x32_bf16 v[16:19], v[206:209], v[190:193], v[16:19]
	ds_read_b128 v[186:189], v151 offset:36864
	v_mfma_f32_16x16x32_bf16 v[8:11], v[214:217], v[190:193], v[8:11]
	v_mfma_f32_16x16x32_bf16 v[4:7], v[206:209], v[198:201], v[4:7]
	ds_read_b128 v[194:197], v151 offset:38912
	v_mfma_f32_16x16x32_bf16 v[0:3], v[214:217], v[198:201], v[0:3]
	s_setprio 0
	s_add_i32 s82, 0, 0x18000
	v_add_u32_e32 v153, s82, v148
	s_barrier
	s_add_u32 s48, s48, 0x100000
	s_addc_u32 s49, s49, 0
	s_mov_b32 m0, s59
	s_nop 0
	global_load_lds_dwordx4 v134, s[48:49]
	s_mov_b32 m0, s60
	s_nop 0
	global_load_lds_dwordx4 v138, s[48:49]
	ds_read_b128 v[174:177], v151 offset:33792
	ds_read_b128 v[182:185], v151 offset:35840
	ds_read_b128 v[190:193], v151 offset:37888
	ds_read_b128 v[198:201], v151 offset:39936
	s_waitcnt lgkmcnt(8)
	s_barrier
	s_waitcnt lgkmcnt(0)
	s_setprio 1
	v_add_u32_e32 v153, 0x1c000, v148
	v_mfma_f32_16x16x32_bf16 v[124:127], v[154:157], v[170:173], v[124:127]
	ds_read_b128 v[202:205], v153
	v_mfma_f32_16x16x32_bf16 v[120:123], v[162:165], v[170:173], v[120:123]
	v_mfma_f32_16x16x32_bf16 v[116:119], v[154:157], v[178:181], v[116:119]
	ds_read_b128 v[206:209], v153 offset:1024
	v_mfma_f32_16x16x32_bf16 v[108:111], v[162:165], v[178:181], v[108:111]
	v_mfma_f32_16x16x32_bf16 v[100:103], v[154:157], v[186:189], v[100:103]
	ds_read_b128 v[210:213], v153 offset:2048
	v_mfma_f32_16x16x32_bf16 v[92:95], v[162:165], v[186:189], v[92:95]
	v_mfma_f32_16x16x32_bf16 v[84:87], v[154:157], v[194:197], v[84:87]
	ds_read_b128 v[214:217], v153 offset:3072
	v_mfma_f32_16x16x32_bf16 v[76:79], v[162:165], v[194:197], v[76:79]
	v_mfma_f32_16x16x32_bf16 v[124:127], v[158:161], v[174:177], v[124:127]
	v_mfma_f32_16x16x32_bf16 v[120:123], v[166:169], v[174:177], v[120:123]
	v_mfma_f32_16x16x32_bf16 v[116:119], v[158:161], v[182:185], v[116:119]
	v_mfma_f32_16x16x32_bf16 v[108:111], v[166:169], v[182:185], v[108:111]
	v_mfma_f32_16x16x32_bf16 v[100:103], v[158:161], v[190:193], v[100:103]
	v_mfma_f32_16x16x32_bf16 v[92:95], v[166:169], v[190:193], v[92:95]
	v_mfma_f32_16x16x32_bf16 v[84:87], v[158:161], v[198:201], v[84:87]
	v_mfma_f32_16x16x32_bf16 v[76:79], v[166:169], v[198:201], v[76:79]
	s_setprio 0
	s_barrier
	s_add_i32 s48, 0, 0x1c000
	s_add_i32 s49, s82, s56
	v_add_u32_e32 v153, s48, v148
	s_add_u32 s98, s46, s8
	s_addc_u32 s99, s47, s9
	s_mov_b32 m0, s49
	s_nop 0
	global_load_lds_dwordx4 v136, s[98:99]
	s_add_i32 m0, s49, 0x2000
	s_nop 0
	global_load_lds_dwordx4 v140, s[98:99]
	s_barrier
	s_waitcnt lgkmcnt(0)
	s_setprio 1
	v_mfma_f32_16x16x32_bf16 v[112:115], v[202:205], v[170:173], v[112:115]
	v_mfma_f32_16x16x32_bf16 v[104:107], v[210:213], v[170:173], v[104:107]
	v_mfma_f32_16x16x32_bf16 v[96:99], v[202:205], v[178:181], v[96:99]
	v_mfma_f32_16x16x32_bf16 v[88:91], v[210:213], v[178:181], v[88:91]
	v_mfma_f32_16x16x32_bf16 v[80:83], v[202:205], v[186:189], v[80:83]
	v_mfma_f32_16x16x32_bf16 v[72:75], v[210:213], v[186:189], v[72:75]
	v_mfma_f32_16x16x32_bf16 v[68:71], v[202:205], v[194:197], v[68:71]
	v_mfma_f32_16x16x32_bf16 v[64:67], v[210:213], v[194:197], v[64:67]
	v_mfma_f32_16x16x32_bf16 v[112:115], v[206:209], v[174:177], v[112:115]
	ds_read_b128 v[170:173], v151 offset:49152
	v_mfma_f32_16x16x32_bf16 v[104:107], v[214:217], v[174:177], v[104:107]
	v_mfma_f32_16x16x32_bf16 v[96:99], v[206:209], v[182:185], v[96:99]
	ds_read_b128 v[178:181], v151 offset:51200
	v_mfma_f32_16x16x32_bf16 v[88:91], v[214:217], v[182:185], v[88:91]
	v_mfma_f32_16x16x32_bf16 v[80:83], v[206:209], v[190:193], v[80:83]
	ds_read_b128 v[186:189], v151 offset:53248
	v_mfma_f32_16x16x32_bf16 v[72:75], v[214:217], v[190:193], v[72:75]
	v_mfma_f32_16x16x32_bf16 v[68:71], v[206:209], v[198:201], v[68:71]
	ds_read_b128 v[194:197], v151 offset:55296
	v_mfma_f32_16x16x32_bf16 v[64:67], v[214:217], v[198:201], v[64:67]
	s_setprio 0
	s_mov_b32 m0, s62
	s_add_u32 s100, s100, s8
	s_addc_u32 s101, s101, s9
	s_barrier
	global_load_lds_dwordx4 v134, s[100:101]
	s_mov_b32 m0, s63
	s_nop 0
	global_load_lds_dwordx4 v138, s[100:101]
	ds_read_b128 v[174:177], v151 offset:50176
	ds_read_b128 v[182:185], v151 offset:52224
	ds_read_b128 v[190:193], v151 offset:54272
	ds_read_b128 v[198:201], v151 offset:56320
	s_waitcnt vmcnt(8)
	s_barrier
; #define PG8_STAGE(bufoff, gbase, voff) do { _Pragma("unroll") for (int _i = 0; _i < 2; ++_i) \
;         __builtin_amdgcn_global_load_lds((const unsigned*)((const char*)(gbase) + (voff)[_i]), (LAS unsigned*)(lds + (bufoff) + ldsw + _i * 8192), 16, 0, 0); } while (0)
; #define PG8_MMA(ai, bj, At, Bt) do { __builtin_amdgcn_s_setprio(1); _Pragma("unroll") for (int m = 0; m < 4; ++m) _Pragma("unroll") for (int n = 0; n < 2; ++n) _Pragma("unroll") for (int k = 0; k < 2; ++k) \
;         acc[ai][bj][m][n] = __builtin_amdgcn_mfma_f32_16x16x32_bf16(Bt[n][k], At[m][k], acc[ai][bj][m][n], 0, 0, 0); __builtin_amdgcn_s_setprio(0); } while (0)
; #define PG8_WAIT_V(n) asm volatile("s_waitcnt vmcnt(" #n ")" ::: "memory")
; #define PG8_WAIT_L(n) asm volatile("s_waitcnt lgkmcnt(" #n ")" ::: "memory")
; #define PG8_BAR __builtin_amdgcn_s_barrier()
; #define PG8_SCHED __builtin_amdgcn_sched_barrier(0)
; template <class Epi, class Job>
; __device__ __forceinline__ void gemm_phase(LAS unsigned char* lds, const Job& S, const Epi& E) {
;     ...
;             PG8_BAR; PG8_WAIT_L(0); PG8_MMA(1, 0, At, B0); PG8_BAR; PG8_SCHED;
;             PG8_STAGE(PG8_SB(1, 1), b3 + hstepB, voffB);
;             PG8_WAIT_V(6); PG8_BAR; PG8_MMA(1, 1, At, B1); PG8_BAR;
;         }
	s_waitcnt lgkmcnt(0)
	s_setprio 1
	v_mfma_f32_16x16x32_bf16 v[60:63], v[154:157], v[170:173], v[60:63]
	v_mfma_f32_16x16x32_bf16 v[56:59], v[162:165], v[170:173], v[56:59]
	v_mfma_f32_16x16x32_bf16 v[52:55], v[154:157], v[178:181], v[52:55]
	v_mfma_f32_16x16x32_bf16 v[44:47], v[162:165], v[178:181], v[44:47]
	v_mfma_f32_16x16x32_bf16 v[36:39], v[154:157], v[186:189], v[36:39]
	v_mfma_f32_16x16x32_bf16 v[28:31], v[162:165], v[186:189], v[28:31]
	v_mfma_f32_16x16x32_bf16 v[20:23], v[154:157], v[194:197], v[20:23]
	v_mfma_f32_16x16x32_bf16 v[12:15], v[162:165], v[194:197], v[12:15]
	v_mfma_f32_16x16x32_bf16 v[60:63], v[158:161], v[174:177], v[60:63]
	v_mfma_f32_16x16x32_bf16 v[56:59], v[166:169], v[174:177], v[56:59]
	v_mfma_f32_16x16x32_bf16 v[52:55], v[158:161], v[182:185], v[52:55]
	v_mfma_f32_16x16x32_bf16 v[44:47], v[166:169], v[182:185], v[44:47]
	v_mfma_f32_16x16x32_bf16 v[36:39], v[158:161], v[190:193], v[36:39]
	v_mfma_f32_16x16x32_bf16 v[28:31], v[166:169], v[190:193], v[28:31]
	v_mfma_f32_16x16x32_bf16 v[20:23], v[158:161], v[198:201], v[20:23]
	v_mfma_f32_16x16x32_bf16 v[12:15], v[166:169], v[198:201], v[12:15]
	s_setprio 0
	s_barrier
	s_add_u32 s46, s46, 0x100080
	s_addc_u32 s47, s47, 0
	s_add_i32 s48, s48, s56
	s_mov_b32 m0, s48
	s_nop 0
	global_load_lds_dwordx4 v136, s[46:47]
	s_add_i32 m0, s48, 0x2000
	s_nop 0
	global_load_lds_dwordx4 v140, s[46:47]
	s_waitcnt vmcnt(6)
	s_barrier
	s_setprio 1
	v_mfma_f32_16x16x32_bf16 v[48:51], v[202:205], v[170:173], v[48:51]
	ds_read_b128 v[154:157], v150
	v_mfma_f32_16x16x32_bf16 v[40:43], v[210:213], v[170:173], v[40:43]
	v_mfma_f32_16x16x32_bf16 v[32:35], v[202:205], v[178:181], v[32:35]
	ds_read_b128 v[158:161], v150 offset:1024
	v_mfma_f32_16x16x32_bf16 v[24:27], v[210:213], v[178:181], v[24:27]
	v_mfma_f32_16x16x32_bf16 v[16:19], v[202:205], v[186:189], v[16:19]
	ds_read_b128 v[162:165], v150 offset:2048
	v_mfma_f32_16x16x32_bf16 v[8:11], v[210:213], v[186:189], v[8:11]
	v_mfma_f32_16x16x32_bf16 v[4:7], v[202:205], v[194:197], v[4:7]
	ds_read_b128 v[166:169], v150 offset:3072
	v_mfma_f32_16x16x32_bf16 v[0:3], v[210:213], v[194:197], v[0:3]
	v_mfma_f32_16x16x32_bf16 v[48:51], v[206:209], v[174:177], v[48:51]
	ds_read_b128 v[170:173], v151
	v_mfma_f32_16x16x32_bf16 v[40:43], v[214:217], v[174:177], v[40:43]
	v_mfma_f32_16x16x32_bf16 v[32:35], v[206:209], v[182:185], v[32:35]
	ds_read_b128 v[178:181], v151 offset:2048
	v_mfma_f32_16x16x32_bf16 v[24:27], v[214:217], v[182:185], v[24:27]
	v_mfma_f32_16x16x32_bf16 v[16:19], v[206:209], v[190:193], v[16:19]
	ds_read_b128 v[186:189], v151 offset:4096
	v_mfma_f32_16x16x32_bf16 v[8:11], v[214:217], v[190:193], v[8:11]
	v_mfma_f32_16x16x32_bf16 v[4:7], v[206:209], v[198:201], v[4:7]
	ds_read_b128 v[194:197], v151 offset:6144
	v_mfma_f32_16x16x32_bf16 v[0:3], v[214:217], v[198:201], v[0:3]
	s_setprio 0
	s_add_i32 s81, s81, 2
	s_add_u32 s36, s36, 0x100
	s_addc_u32 s37, s37, 0
	s_add_u32 s79, s79, 0x100
	s_addc_u32 s80, s80, 0
	s_cmp_gt_u32 s81, 61
	s_barrier
	s_cbranch_scc0 .LBB0_457
; __device__ __forceinline__ unsigned cvt_pk_bf16(float lo, float hi) { unsigned r; asm volatile("v_cvt_pk_bf16_f32 %0, %1, %2" : "=v"(r) : "v"(lo), "v"(hi)); return r; }
;     __device__ __forceinline__ void operator()(const f32x4 (&acc)[2][2][4][2], const Unit& u, int wr, int wc, int fr, int fq) const {
;         const int row0 = u.orow + wr * 64 + fr, col0 = u.ocol + wc * 32 + 8 * fq;
; #pragma unroll
;         for (int ai = 0; ai < 2; ++ai)
; #pragma unroll
;             for (int m = 0; m < 4; ++m) { bf16_t* rowp = O + (size_t)(row0 + ai * HALF + m * 16) * ldc + col0;
; #pragma unroll
;                 for (int bj = 0; bj < 2; ++bj) { const f32x4 v0 = acc[ai][bj][m][0], v1 = acc[ai][bj][m][1];
;                     u32x4 w; w.x = cvt_pk_bf16(v0[0], v0[1]); w.y = cvt_pk_bf16(v0[2], v0[3]); w.z = cvt_pk_bf16(v1[0], v1[1]); w.w = cvt_pk_bf16(v1[2], v1[3]);
;                     if (nt) __builtin_nontemporal_store(w, (u32x4*)(rowp + bj * HALF)); else *(u32x4*)(rowp + bj * HALF) = w; } }
	s_waitcnt lgkmcnt(0)
	v_add_u32_e32 v146, s78, v131
	v_ashrrev_i32_e32 v147, 31, v146
	v_add_u32_e32 v154, s77, v149
	v_lshlrev_b64 v[146:147], 13, v[146:147]
	v_ashrrev_i32_e32 v155, 31, v154
	v_lshl_add_u64 v[146:147], s[18:19], 0, v[146:147]
	v_lshl_add_u64 v[146:147], v[154:155], 1, v[146:147]
	v_cvt_pk_bf16_f32 v124, v124, v125
	v_cvt_pk_bf16_f32 v125, v126, v127
	v_cvt_pk_bf16_f32 v126, v120, v121
	v_cvt_pk_bf16_f32 v127, v122, v123
	global_store_dwordx4 v[146:147], v[124:127], off
	v_cvt_pk_bf16_f32 v112, v112, v113
	v_cvt_pk_bf16_f32 v113, v114, v115
	v_cvt_pk_bf16_f32 v114, v104, v105
	v_cvt_pk_bf16_f32 v115, v106, v107
	global_store_dwordx4 v[146:147], v[112:115], off offset:256
	v_cvt_pk_bf16_f32 v104, v116, v117
	v_cvt_pk_bf16_f32 v105, v118, v119
	v_cvt_pk_bf16_f32 v106, v108, v109
	v_add_co_u32_e32 v108, vcc, s68, v146
	s_nop 0
	v_lshl_add_u64 v[112:113], v[146:147], 0, s[10:11]
	v_addc_co_u32_e32 v109, vcc, 0, v147, vcc
	v_cvt_pk_bf16_f32 v107, v110, v111
	global_store_dwordx4 v[108:109], v[104:107], off
	v_cvt_pk_bf16_f32 v96, v96, v97
	v_cvt_pk_bf16_f32 v97, v98, v99
	v_cvt_pk_bf16_f32 v98, v88, v89
	v_cvt_pk_bf16_f32 v99, v90, v91
	global_store_dwordx4 v[112:113], v[96:99], off offset:256
	v_cvt_pk_bf16_f32 v88, v100, v101
	v_cvt_pk_bf16_f32 v89, v102, v103
	v_cvt_pk_bf16_f32 v90, v92, v93
	v_add_co_u32_e32 v92, vcc, s69, v146
	s_nop 0
	v_lshl_add_u64 v[96:97], v[146:147], 0, s[12:13]
	v_addc_co_u32_e32 v93, vcc, 0, v147, vcc
	v_cvt_pk_bf16_f32 v91, v94, v95
	global_store_dwordx4 v[92:93], v[88:91], off
	v_cvt_pk_bf16_f32 v80, v80, v81
	v_cvt_pk_bf16_f32 v81, v82, v83
	v_cvt_pk_bf16_f32 v82, v72, v73
	v_cvt_pk_bf16_f32 v83, v74, v75
	global_store_dwordx4 v[96:97], v[80:83], off offset:256
	v_cvt_pk_bf16_f32 v72, v84, v85
	v_cvt_pk_bf16_f32 v73, v86, v87
	v_cvt_pk_bf16_f32 v74, v76, v77
	v_add_co_u32_e32 v76, vcc, s70, v146
	s_nop 0
	v_lshl_add_u64 v[80:81], v[146:147], 0, s[20:21]
	v_addc_co_u32_e32 v77, vcc, 0, v147, vcc
	v_cvt_pk_bf16_f32 v75, v78, v79
	global_store_dwordx4 v[76:77], v[72:75], off
	v_cvt_pk_bf16_f32 v68, v68, v69
	v_cvt_pk_bf16_f32 v69, v70, v71
	v_cvt_pk_bf16_f32 v70, v64, v65
	v_cvt_pk_bf16_f32 v71, v66, v67
	global_store_dwordx4 v[80:81], v[68:71], off offset:256
	v_cvt_pk_bf16_f32 v60, v60, v61
	v_cvt_pk_bf16_f32 v61, v62, v63
	v_cvt_pk_bf16_f32 v62, v56, v57
	v_add_co_u32_e32 v56, vcc, s71, v146
	v_lshl_add_u64 v[64:65], v[146:147], 0, s[6:7]
	s_nop 0
	v_addc_co_u32_e32 v57, vcc, 0, v147, vcc
	v_cvt_pk_bf16_f32 v63, v58, v59
	global_store_dwordx4 v[56:57], v[60:63], off
	v_cvt_pk_bf16_f32 v48, v48, v49
	v_cvt_pk_bf16_f32 v49, v50, v51
	v_cvt_pk_bf16_f32 v50, v40, v41
	v_cvt_pk_bf16_f32 v51, v42, v43
	global_store_dwordx4 v[64:65], v[48:51], off offset:256
	v_cvt_pk_bf16_f32 v40, v52, v53
	v_cvt_pk_bf16_f32 v41, v54, v55
	v_cvt_pk_bf16_f32 v42, v44, v45
	v_add_co_u32_e32 v44, vcc, s72, v146
	s_nop 0
	v_lshl_add_u64 v[48:49], v[146:147], 0, s[22:23]
	v_addc_co_u32_e32 v45, vcc, 0, v147, vcc
	v_cvt_pk_bf16_f32 v43, v46, v47
	global_store_dwordx4 v[44:45], v[40:43], off
	v_cvt_pk_bf16_f32 v32, v32, v33
	v_cvt_pk_bf16_f32 v33, v34, v35
	v_cvt_pk_bf16_f32 v34, v24, v25
	v_cvt_pk_bf16_f32 v35, v26, v27
	global_store_dwordx4 v[48:49], v[32:35], off offset:256
	v_cvt_pk_bf16_f32 v24, v36, v37
	v_cvt_pk_bf16_f32 v25, v38, v39
	v_cvt_pk_bf16_f32 v26, v28, v29
	v_add_co_u32_e32 v28, vcc, s73, v146
	s_nop 0
	v_lshl_add_u64 v[32:33], v[146:147], 0, s[24:25]
	v_addc_co_u32_e32 v29, vcc, 0, v147, vcc
	v_cvt_pk_bf16_f32 v27, v30, v31
	global_store_dwordx4 v[28:29], v[24:27], off
	v_cvt_pk_bf16_f32 v16, v16, v17
	v_cvt_pk_bf16_f32 v17, v18, v19
	v_cvt_pk_bf16_f32 v18, v8, v9
	v_cvt_pk_bf16_f32 v19, v10, v11
	global_store_dwordx4 v[32:33], v[16:19], off offset:256
	v_cvt_pk_bf16_f32 v8, v20, v21
	v_cvt_pk_bf16_f32 v9, v22, v23
	v_cvt_pk_bf16_f32 v10, v12, v13
	v_add_co_u32_e32 v12, vcc, s74, v146
	s_nop 0
	v_lshl_add_u64 v[16:17], v[146:147], 0, s[26:27]
	v_addc_co_u32_e32 v13, vcc, 0, v147, vcc
	s_and_b64 vcc, exec, s[4:5]
	s_mov_b32 s77, s76
	s_mov_b32 s78, s75
	s_mov_b64 s[46:47], s[30:31]
	s_mov_b64 s[36:37], s[28:29]
	v_cvt_pk_bf16_f32 v11, v14, v15
	global_store_dwordx4 v[12:13], v[8:11], off
	v_cvt_pk_bf16_f32 v4, v4, v5
	v_cvt_pk_bf16_f32 v5, v6, v7
	v_cvt_pk_bf16_f32 v6, v0, v1
	v_cvt_pk_bf16_f32 v7, v2, v3
	global_store_dwordx4 v[16:17], v[4:7], off offset:256
	s_cbranch_vccz .LBB0_450
	s_waitcnt vmcnt(0)
	s_cmpk_gt_u32 s50, 0xff
	s_cbranch_scc1 .LBB0_461
	s_barrier
